# plus prep phase: trailing-window row loads issued together (up to 15 in flight) then accumulated in original order
# speedup vs baseline: 1.0318x; 1.0211x over previous
; __device__ __forceinline__ unsigned cvt_pk_bf16(float lo, float hi) { f32x2_cv v = {lo, hi}; bf16x2_cv b = __builtin_convertvector(v, bf16x2_cv); return __builtin_bit_cast(unsigned, b); }
; __device__ __forceinline__ float bf_lo(unsigned u) { return __uint_as_float(u << 16); }
; __device__ __forceinline__ float bf_hi(unsigned u) { return __uint_as_float(u & 0xffff0000u); }
; __global__ void __launch_bounds__(NTHR) fwd_kernel(Args args) {
;     ...
;                 { const int tp = t & (SEQ - 1), wdw = 2 << (lane >> 4), cnt = (tp + 1) < wdw ? (tp + 1) : wdw;
;                   float a[8]; const u32x4 cur = *(const u32x4*)(zr + 512 + 8 * lane);
; #pragma unroll
;                   for (int e = 0; e < 4; ++e) { a[2 * e] = bf_lo(cur[e]); a[2 * e + 1] = bf_hi(cur[e]); }
;                   float sm[8];
; #pragma unroll
;                   for (int e = 0; e < 8; ++e) sm[e] = a[e];
;                   for (int j = 1; j < cnt; ++j) { const u32x4 pv = *(const u32x4*)(zr - (size_t)j * 1024 + 512 + 8 * lane);
; #pragma unroll
;                       for (int e = 0; e < 4; ++e) { sm[2 * e] += bf_lo(pv[e]); sm[2 * e + 1] += bf_hi(pv[e]); } }
;                   const float ic = 1.0f / (float)cnt; u32x4 o;
; #pragma unroll
;                   for (int e = 0; e < 4; ++e) o[e] = cvt_pk_bf16(sm[2 * e] * ic - a[2 * e], sm[2 * e + 1] * ic - a[2 * e + 1]);
;                   *(u32x4*)(PO + (size_t)t * 512 + 8 * lane) = o; }
.LBB0_465:
	s_mov_b64 s[44:45], exec
	s_movk_i32 s18, 0xf800
	s_mov_b32 s19, -1
	global_load_dwordx4 v[64:67], v[42:43], off
	v_lshl_add_u64 v[42:43], v[42:43], 0, s[18:19]
	v_cmp_le_u32_e32 vcc, 2, v2
	s_nop 1
	s_and_b64 exec, s[44:45], vcc
	s_cbranch_execz .Lpool_issued
	global_load_dwordx4 v[68:71], v[42:43], off
	v_lshl_add_u64 v[42:43], v[42:43], 0, s[18:19]
	v_cmp_le_u32_e32 vcc, 3, v2
	s_nop 1
	s_and_b64 exec, s[44:45], vcc
	s_cbranch_execz .Lpool_issued
	global_load_dwordx4 v[72:75], v[42:43], off
	v_lshl_add_u64 v[42:43], v[42:43], 0, s[18:19]
	v_cmp_le_u32_e32 vcc, 4, v2
	s_nop 1
	s_and_b64 exec, s[44:45], vcc
	s_cbranch_execz .Lpool_issued
	global_load_dwordx4 v[76:79], v[42:43], off
	v_lshl_add_u64 v[42:43], v[42:43], 0, s[18:19]
	v_cmp_le_u32_e32 vcc, 5, v2
	s_nop 1
	s_and_b64 exec, s[44:45], vcc
	s_cbranch_execz .Lpool_issued
	global_load_dwordx4 v[80:83], v[42:43], off
	v_lshl_add_u64 v[42:43], v[42:43], 0, s[18:19]
	v_cmp_le_u32_e32 vcc, 6, v2
	s_nop 1
	s_and_b64 exec, s[44:45], vcc
	s_cbranch_execz .Lpool_issued
	global_load_dwordx4 v[84:87], v[42:43], off
	v_lshl_add_u64 v[42:43], v[42:43], 0, s[18:19]
	v_cmp_le_u32_e32 vcc, 7, v2
	s_nop 1
	s_and_b64 exec, s[44:45], vcc
	s_cbranch_execz .Lpool_issued
	global_load_dwordx4 v[88:91], v[42:43], off
	v_lshl_add_u64 v[42:43], v[42:43], 0, s[18:19]
	v_cmp_le_u32_e32 vcc, 8, v2
	s_nop 1
	s_and_b64 exec, s[44:45], vcc
	s_cbranch_execz .Lpool_issued
	global_load_dwordx4 v[92:95], v[42:43], off
	v_lshl_add_u64 v[42:43], v[42:43], 0, s[18:19]
	v_cmp_le_u32_e32 vcc, 9, v2
	s_nop 1
	s_and_b64 exec, s[44:45], vcc
	s_cbranch_execz .Lpool_issued
	global_load_dwordx4 v[96:99], v[42:43], off
	v_lshl_add_u64 v[42:43], v[42:43], 0, s[18:19]
	v_cmp_le_u32_e32 vcc, 10, v2
	s_nop 1
	s_and_b64 exec, s[44:45], vcc
	s_cbranch_execz .Lpool_issued
	global_load_dwordx4 v[100:103], v[42:43], off
	v_lshl_add_u64 v[42:43], v[42:43], 0, s[18:19]
	v_cmp_le_u32_e32 vcc, 11, v2
	s_nop 1
	s_and_b64 exec, s[44:45], vcc
	s_cbranch_execz .Lpool_issued
	global_load_dwordx4 v[104:107], v[42:43], off
	v_lshl_add_u64 v[42:43], v[42:43], 0, s[18:19]
	v_cmp_le_u32_e32 vcc, 12, v2
	s_nop 1
	s_and_b64 exec, s[44:45], vcc
	s_cbranch_execz .Lpool_issued
	global_load_dwordx4 v[108:111], v[42:43], off
	v_lshl_add_u64 v[42:43], v[42:43], 0, s[18:19]
	v_cmp_le_u32_e32 vcc, 13, v2
	s_nop 1
	s_and_b64 exec, s[44:45], vcc
	s_cbranch_execz .Lpool_issued
	global_load_dwordx4 v[112:115], v[42:43], off
	v_lshl_add_u64 v[42:43], v[42:43], 0, s[18:19]
	v_cmp_le_u32_e32 vcc, 14, v2
	s_nop 1
	s_and_b64 exec, s[44:45], vcc
	s_cbranch_execz .Lpool_issued
	global_load_dwordx4 v[116:119], v[42:43], off
	v_lshl_add_u64 v[42:43], v[42:43], 0, s[18:19]
	v_cmp_le_u32_e32 vcc, 15, v2
	s_nop 1
	s_and_b64 exec, s[44:45], vcc
	s_cbranch_execz .Lpool_issued
	global_load_dwordx4 v[120:123], v[42:43], off
	v_lshl_add_u64 v[42:43], v[42:43], 0, s[18:19]
.Lpool_issued:
	s_mov_b64 exec, s[44:45]
	s_waitcnt vmcnt(0)
	v_lshlrev_b32_e32 v58, 16, v64
	v_and_b32_e32 v59, 0xffff0000, v64
	v_lshlrev_b32_e32 v54, 16, v65
	v_and_b32_e32 v55, 0xffff0000, v65
	v_pk_add_f32 v[32:33], v[32:33], v[54:55]
	v_lshlrev_b32_e32 v54, 16, v66
	v_and_b32_e32 v55, 0xffff0000, v66
	v_pk_add_f32 v[38:39], v[38:39], v[54:55]
	v_lshlrev_b32_e32 v54, 16, v67
	v_and_b32_e32 v55, 0xffff0000, v67
	v_pk_add_f32 v[36:37], v[36:37], v[58:59]
	v_pk_add_f32 v[40:41], v[40:41], v[54:55]
	v_cmp_le_u32_e32 vcc, 2, v2
	s_nop 1
	s_and_b64 exec, s[44:45], vcc
	s_cbranch_execz .Lpool_done
	v_lshlrev_b32_e32 v58, 16, v68
	v_and_b32_e32 v59, 0xffff0000, v68
	v_lshlrev_b32_e32 v54, 16, v69
	v_and_b32_e32 v55, 0xffff0000, v69
	v_pk_add_f32 v[32:33], v[32:33], v[54:55]
	v_lshlrev_b32_e32 v54, 16, v70
	v_and_b32_e32 v55, 0xffff0000, v70
	v_pk_add_f32 v[38:39], v[38:39], v[54:55]
	v_lshlrev_b32_e32 v54, 16, v71
	v_and_b32_e32 v55, 0xffff0000, v71
	v_pk_add_f32 v[36:37], v[36:37], v[58:59]
	v_pk_add_f32 v[40:41], v[40:41], v[54:55]
	v_cmp_le_u32_e32 vcc, 3, v2
	s_nop 1
	s_and_b64 exec, s[44:45], vcc
	s_cbranch_execz .Lpool_done
	v_lshlrev_b32_e32 v58, 16, v72
	v_and_b32_e32 v59, 0xffff0000, v72
	v_lshlrev_b32_e32 v54, 16, v73
	v_and_b32_e32 v55, 0xffff0000, v73
	v_pk_add_f32 v[32:33], v[32:33], v[54:55]
	v_lshlrev_b32_e32 v54, 16, v74
	v_and_b32_e32 v55, 0xffff0000, v74
	v_pk_add_f32 v[38:39], v[38:39], v[54:55]
	v_lshlrev_b32_e32 v54, 16, v75
	v_and_b32_e32 v55, 0xffff0000, v75
	v_pk_add_f32 v[36:37], v[36:37], v[58:59]
	v_pk_add_f32 v[40:41], v[40:41], v[54:55]
	v_cmp_le_u32_e32 vcc, 4, v2
	s_nop 1
	s_and_b64 exec, s[44:45], vcc
	s_cbranch_execz .Lpool_done
	v_lshlrev_b32_e32 v58, 16, v76
	v_and_b32_e32 v59, 0xffff0000, v76
	v_lshlrev_b32_e32 v54, 16, v77
	v_and_b32_e32 v55, 0xffff0000, v77
	v_pk_add_f32 v[32:33], v[32:33], v[54:55]
	v_lshlrev_b32_e32 v54, 16, v78
	v_and_b32_e32 v55, 0xffff0000, v78
	v_pk_add_f32 v[38:39], v[38:39], v[54:55]
	v_lshlrev_b32_e32 v54, 16, v79
	v_and_b32_e32 v55, 0xffff0000, v79
	v_pk_add_f32 v[36:37], v[36:37], v[58:59]
	v_pk_add_f32 v[40:41], v[40:41], v[54:55]
	v_cmp_le_u32_e32 vcc, 5, v2
	s_nop 1
	s_and_b64 exec, s[44:45], vcc
	s_cbranch_execz .Lpool_done
	v_lshlrev_b32_e32 v58, 16, v80
	v_and_b32_e32 v59, 0xffff0000, v80
	v_lshlrev_b32_e32 v54, 16, v81
	v_and_b32_e32 v55, 0xffff0000, v81
	v_pk_add_f32 v[32:33], v[32:33], v[54:55]
	v_lshlrev_b32_e32 v54, 16, v82
	v_and_b32_e32 v55, 0xffff0000, v82
	v_pk_add_f32 v[38:39], v[38:39], v[54:55]
	v_lshlrev_b32_e32 v54, 16, v83
	v_and_b32_e32 v55, 0xffff0000, v83
	v_pk_add_f32 v[36:37], v[36:37], v[58:59]
	v_pk_add_f32 v[40:41], v[40:41], v[54:55]
	v_cmp_le_u32_e32 vcc, 6, v2
	s_nop 1
	s_and_b64 exec, s[44:45], vcc
	s_cbranch_execz .Lpool_done
; __device__ __forceinline__ float bf_lo(unsigned u) { return __uint_as_float(u << 16); }
; __device__ __forceinline__ float bf_hi(unsigned u) { return __uint_as_float(u & 0xffff0000u); }
; __global__ void __launch_bounds__(NTHR) fwd_kernel(Args args) {
;     ...
;                   for (int j = 1; j < cnt; ++j) { const u32x4 pv = *(const u32x4*)(zr - (size_t)j * 1024 + 512 + 8 * lane);
; #pragma unroll
;                       for (int e = 0; e < 4; ++e) { sm[2 * e] += bf_lo(pv[e]); sm[2 * e + 1] += bf_hi(pv[e]); } }
	v_lshlrev_b32_e32 v58, 16, v84
	v_and_b32_e32 v59, 0xffff0000, v84
	v_lshlrev_b32_e32 v54, 16, v85
	v_and_b32_e32 v55, 0xffff0000, v85
	v_pk_add_f32 v[32:33], v[32:33], v[54:55]
	v_lshlrev_b32_e32 v54, 16, v86
	v_and_b32_e32 v55, 0xffff0000, v86
	v_pk_add_f32 v[38:39], v[38:39], v[54:55]
	v_lshlrev_b32_e32 v54, 16, v87
	v_and_b32_e32 v55, 0xffff0000, v87
	v_pk_add_f32 v[36:37], v[36:37], v[58:59]
	v_pk_add_f32 v[40:41], v[40:41], v[54:55]
	v_cmp_le_u32_e32 vcc, 7, v2
	s_nop 1
	s_and_b64 exec, s[44:45], vcc
	s_cbranch_execz .Lpool_done
	v_lshlrev_b32_e32 v58, 16, v88
	v_and_b32_e32 v59, 0xffff0000, v88
	v_lshlrev_b32_e32 v54, 16, v89
	v_and_b32_e32 v55, 0xffff0000, v89
	v_pk_add_f32 v[32:33], v[32:33], v[54:55]
	v_lshlrev_b32_e32 v54, 16, v90
	v_and_b32_e32 v55, 0xffff0000, v90
	v_pk_add_f32 v[38:39], v[38:39], v[54:55]
	v_lshlrev_b32_e32 v54, 16, v91
	v_and_b32_e32 v55, 0xffff0000, v91
	v_pk_add_f32 v[36:37], v[36:37], v[58:59]
	v_pk_add_f32 v[40:41], v[40:41], v[54:55]
	v_cmp_le_u32_e32 vcc, 8, v2
	s_nop 1
	s_and_b64 exec, s[44:45], vcc
	s_cbranch_execz .Lpool_done
	v_lshlrev_b32_e32 v58, 16, v92
	v_and_b32_e32 v59, 0xffff0000, v92
	v_lshlrev_b32_e32 v54, 16, v93
	v_and_b32_e32 v55, 0xffff0000, v93
	v_pk_add_f32 v[32:33], v[32:33], v[54:55]
	v_lshlrev_b32_e32 v54, 16, v94
	v_and_b32_e32 v55, 0xffff0000, v94
	v_pk_add_f32 v[38:39], v[38:39], v[54:55]
	v_lshlrev_b32_e32 v54, 16, v95
	v_and_b32_e32 v55, 0xffff0000, v95
	v_pk_add_f32 v[36:37], v[36:37], v[58:59]
	v_pk_add_f32 v[40:41], v[40:41], v[54:55]
	v_cmp_le_u32_e32 vcc, 9, v2
	s_nop 1
	s_and_b64 exec, s[44:45], vcc
	s_cbranch_execz .Lpool_done
	v_lshlrev_b32_e32 v58, 16, v96
	v_and_b32_e32 v59, 0xffff0000, v96
	v_lshlrev_b32_e32 v54, 16, v97
	v_and_b32_e32 v55, 0xffff0000, v97
	v_pk_add_f32 v[32:33], v[32:33], v[54:55]
	v_lshlrev_b32_e32 v54, 16, v98
	v_and_b32_e32 v55, 0xffff0000, v98
	v_pk_add_f32 v[38:39], v[38:39], v[54:55]
	v_lshlrev_b32_e32 v54, 16, v99
	v_and_b32_e32 v55, 0xffff0000, v99
	v_pk_add_f32 v[36:37], v[36:37], v[58:59]
	v_pk_add_f32 v[40:41], v[40:41], v[54:55]
	v_cmp_le_u32_e32 vcc, 10, v2
	s_nop 1
	s_and_b64 exec, s[44:45], vcc
	s_cbranch_execz .Lpool_done
	v_lshlrev_b32_e32 v58, 16, v100
	v_and_b32_e32 v59, 0xffff0000, v100
	v_lshlrev_b32_e32 v54, 16, v101
	v_and_b32_e32 v55, 0xffff0000, v101
	v_pk_add_f32 v[32:33], v[32:33], v[54:55]
	v_lshlrev_b32_e32 v54, 16, v102
	v_and_b32_e32 v55, 0xffff0000, v102
	v_pk_add_f32 v[38:39], v[38:39], v[54:55]
	v_lshlrev_b32_e32 v54, 16, v103
	v_and_b32_e32 v55, 0xffff0000, v103
	v_pk_add_f32 v[36:37], v[36:37], v[58:59]
	v_pk_add_f32 v[40:41], v[40:41], v[54:55]
	v_cmp_le_u32_e32 vcc, 11, v2
	s_nop 1
	s_and_b64 exec, s[44:45], vcc
	s_cbranch_execz .Lpool_done
	v_lshlrev_b32_e32 v58, 16, v104
	v_and_b32_e32 v59, 0xffff0000, v104
	v_lshlrev_b32_e32 v54, 16, v105
	v_and_b32_e32 v55, 0xffff0000, v105
	v_pk_add_f32 v[32:33], v[32:33], v[54:55]
	v_lshlrev_b32_e32 v54, 16, v106
	v_and_b32_e32 v55, 0xffff0000, v106
	v_pk_add_f32 v[38:39], v[38:39], v[54:55]
	v_lshlrev_b32_e32 v54, 16, v107
	v_and_b32_e32 v55, 0xffff0000, v107
	v_pk_add_f32 v[36:37], v[36:37], v[58:59]
	v_pk_add_f32 v[40:41], v[40:41], v[54:55]
	v_cmp_le_u32_e32 vcc, 12, v2
	s_nop 1
	s_and_b64 exec, s[44:45], vcc
	s_cbranch_execz .Lpool_done
	v_lshlrev_b32_e32 v58, 16, v108
	v_and_b32_e32 v59, 0xffff0000, v108
	v_lshlrev_b32_e32 v54, 16, v109
	v_and_b32_e32 v55, 0xffff0000, v109
	v_pk_add_f32 v[32:33], v[32:33], v[54:55]
	v_lshlrev_b32_e32 v54, 16, v110
	v_and_b32_e32 v55, 0xffff0000, v110
	v_pk_add_f32 v[38:39], v[38:39], v[54:55]
	v_lshlrev_b32_e32 v54, 16, v111
	v_and_b32_e32 v55, 0xffff0000, v111
	v_pk_add_f32 v[36:37], v[36:37], v[58:59]
	v_pk_add_f32 v[40:41], v[40:41], v[54:55]
	v_cmp_le_u32_e32 vcc, 13, v2
	s_nop 1
	s_and_b64 exec, s[44:45], vcc
	s_cbranch_execz .Lpool_done
	v_lshlrev_b32_e32 v58, 16, v112
	v_and_b32_e32 v59, 0xffff0000, v112
	v_lshlrev_b32_e32 v54, 16, v113
	v_and_b32_e32 v55, 0xffff0000, v113
	v_pk_add_f32 v[32:33], v[32:33], v[54:55]
	v_lshlrev_b32_e32 v54, 16, v114
	v_and_b32_e32 v55, 0xffff0000, v114
	v_pk_add_f32 v[38:39], v[38:39], v[54:55]
	v_lshlrev_b32_e32 v54, 16, v115
	v_and_b32_e32 v55, 0xffff0000, v115
	v_pk_add_f32 v[36:37], v[36:37], v[58:59]
	v_pk_add_f32 v[40:41], v[40:41], v[54:55]
	v_cmp_le_u32_e32 vcc, 14, v2
	s_nop 1
	s_and_b64 exec, s[44:45], vcc
	s_cbranch_execz .Lpool_done
	v_lshlrev_b32_e32 v58, 16, v116
	v_and_b32_e32 v59, 0xffff0000, v116
	v_lshlrev_b32_e32 v54, 16, v117
	v_and_b32_e32 v55, 0xffff0000, v117
	v_pk_add_f32 v[32:33], v[32:33], v[54:55]
	v_lshlrev_b32_e32 v54, 16, v118
	v_and_b32_e32 v55, 0xffff0000, v118
	v_pk_add_f32 v[38:39], v[38:39], v[54:55]
	v_lshlrev_b32_e32 v54, 16, v119
	v_and_b32_e32 v55, 0xffff0000, v119
	v_pk_add_f32 v[36:37], v[36:37], v[58:59]
	v_pk_add_f32 v[40:41], v[40:41], v[54:55]
	v_cmp_le_u32_e32 vcc, 15, v2
	s_nop 1
	s_and_b64 exec, s[44:45], vcc
	s_cbranch_execz .Lpool_done
	v_lshlrev_b32_e32 v58, 16, v120
	v_and_b32_e32 v59, 0xffff0000, v120
	v_lshlrev_b32_e32 v54, 16, v121
	v_and_b32_e32 v55, 0xffff0000, v121
	v_pk_add_f32 v[32:33], v[32:33], v[54:55]
	v_lshlrev_b32_e32 v54, 16, v122
	v_and_b32_e32 v55, 0xffff0000, v122
	v_pk_add_f32 v[38:39], v[38:39], v[54:55]
	v_lshlrev_b32_e32 v54, 16, v123
	v_and_b32_e32 v55, 0xffff0000, v123
	v_pk_add_f32 v[36:37], v[36:37], v[58:59]
	v_pk_add_f32 v[40:41], v[40:41], v[54:55]
.Lpool_done:
	s_mov_b64 exec, s[44:45]
	s_branch .LBB0_460
